# producer y-output block of the first half step moved to the step tail (off the path to the operand writes)
# speedup vs baseline: 1.0234x; 1.0092x over previous
; #define LAS __attribute__((address_space(3)))
; __device__ __forceinline__ float f16_to_f(unsigned short h) { return (float)__builtin_bit_cast(_Float16, h); }
; __device__ __forceinline__ float scan_prepare(const ScanRegs& R, const u32x2 qr_, const u32x2 qk_, const u32x2 qv_, LAS float* slot, int cq, const f32x4 mur, const f32x4 muk, const f32x4 muv, const f32x4 kkc, const f32x4 kac, const f32x4 rkc) {
;     float pr[4], pk[4], pv[4], qr[4], qk[4], qv[4], av[4], om[4];
;     unpack4(R.pr, pr); unpack4(R.pk, pk); unpack4(R.pv, pv); unpack4(qr_, qr); unpack4(qk_, qk); unpack4(qv_, qv); unpack4(R.as, av);
;     om[0] = f16_to_f((unsigned short)(R.wl.x & 0xffffu)); om[1] = f16_to_f((unsigned short)(R.wl.x >> 16)); om[2] = f16_to_f((unsigned short)(R.wl.y & 0xffffu)); om[3] = f16_to_f((unsigned short)(R.wl.y >> 16));
;     float rr[4], vv[4], kn[4], k2[4], dec[4], bu[4];
;     float ssq = 0.f, bon = 0.f, c1 = 0.f, c2 = 0.f;
; #pragma unroll
;     for (int j = 0; j < 4; ++j) {
;         rr[j] = pr[j] + (qr[j] - pr[j]) * mur[j]; const float kk0 = pk[j] + (qk[j] - pk[j]) * muk[j]; vv[j] = pv[j] + (qv[j] - pv[j]) * muv[j];
;         dec[j] = 1.0f - om[j];
;         kn[j] = kk0 * kkc[j]; ssq += kn[j] * kn[j];
;         k2[j] = kk0 * (1.0f + (av[j] - 1.0f) * kac[j]);
;         const float t = rr[j] * k2[j]; bon += t * rkc[j]; c2 += t;
;         bu[j] = kn[j] * av[j]; c1 += bu[j] * rr[j];
;     }
;     ssq += dpp_f<0x121>(ssq); bon += dpp_f<0x121>(bon); c1 += dpp_f<0x121>(c1); c2 += dpp_f<0x121>(c2);
;     ssq += dpp_f<0x122>(ssq); bon += dpp_f<0x122>(bon); c1 += dpp_f<0x122>(c1); c2 += dpp_f<0x122>(c2);
;     ssq += dpp_f<0x124>(ssq); bon += dpp_f<0x124>(bon); c1 += dpp_f<0x124>(c1); c2 += dpp_f<0x124>(c2);
;     ssq += dpp_f<0x128>(ssq); bon += dpp_f<0x128>(bon); c1 += dpp_f<0x128>(c1); c2 += dpp_f<0x128>(c2);
;     const float inv = __builtin_amdgcn_rsqf(fmaxf(ssq, 1e-24f));
;     f32x4 o_al, o_be, o_wr;
; #pragma unroll
;     for (int j = 0; j < 4; ++j) { o_al[j] = -(kn[j] * inv); o_be[j] = bu[j] * inv; o_wr[j] = dec[j] * rr[j]; }
;     LAS f32x4* s4 = (LAS f32x4*)slot;
;     s4[cq] = (f32x4){dec[0], dec[1], dec[2], dec[3]}; s4[16 + cq] = (f32x4){k2[0], k2[1], k2[2], k2[3]}; s4[32 + cq] = o_al; s4[48 + cq] = o_be; s4[64 + cq] = o_wr;
;     s4[80 + cq] = (f32x4){vv[0], vv[1], vv[2], vv[3]};
;     if (cq == 0) *(LAS f32x2*)(slot + 384) = (f32x2){c1 * inv, c2};
.LBB0_1107:
.LBB0_1109:
	s_waitcnt vmcnt(8)
	v_lshlrev_b32_e32 v108, 16, v46
	v_and_b32_e32 v109, 0xffff0000, v46
	v_lshlrev_b32_e32 v110, 16, v38
	v_and_b32_e32 v111, 0xffff0000, v38
	v_pk_add_f32 v[110:111], v[110:111], v[108:109] neg_lo:[0,1] neg_hi:[0,1]
	v_lshlrev_b32_e32 v140, 16, v39
	v_pk_fma_f32 v[144:145], v[6:7], v[110:111], v[108:109]
	v_lshlrev_b32_e32 v110, 16, v47
	v_and_b32_e32 v111, 0xffff0000, v47
	v_and_b32_e32 v141, 0xffff0000, v39
	v_pk_add_f32 v[140:141], v[140:141], v[110:111] neg_lo:[0,1] neg_hi:[0,1]
	v_lshlrev_b32_e32 v118, 16, v40
	v_and_b32_e32 v119, 0xffff0000, v40
	v_pk_fma_f32 v[146:147], v[8:9], v[140:141], v[110:111]
	v_lshlrev_b32_e32 v140, 16, v34
	v_and_b32_e32 v141, 0xffff0000, v34
	s_waitcnt vmcnt(3)
	v_lshlrev_b32_e32 v142, 16, v48
	v_and_b32_e32 v143, 0xffff0000, v48
	v_pk_add_f32 v[140:141], v[140:141], v[118:119] neg_lo:[0,1] neg_hi:[0,1]
	v_pk_add_f32 v[148:149], v[142:143], -1.0 op_sel_hi:[1,0]
	v_pk_fma_f32 v[140:141], v[2:3], v[140:141], v[118:119]
	v_pk_fma_f32 v[148:149], v[18:19], v[148:149], 1.0 op_sel_hi:[1,1,0]
	v_pk_mul_f32 v[154:155], v[14:15], v[140:141]
	v_pk_mul_f32 v[148:149], v[148:149], v[140:141]
	v_cvt_f32_f16_sdwa v141, v44 dst_sel:DWORD dst_unused:UNUSED_PAD src0_sel:WORD_1
	v_cvt_f32_f16_e32 v140, v44
	v_lshlrev_b32_e32 v114, 16, v36
	v_and_b32_e32 v115, 0xffff0000, v36
	v_lshlrev_b32_e32 v156, 16, v42
	v_and_b32_e32 v157, 0xffff0000, v42
	v_pk_add_f32 v[152:153], v[140:141], 1.0 op_sel_hi:[1,0] neg_lo:[1,0] neg_hi:[1,0]
	v_pk_add_f32 v[140:141], v[156:157], v[114:115] neg_lo:[0,1] neg_hi:[0,1]
	v_lshlrev_b32_e32 v116, 16, v41
	v_pk_fma_f32 v[164:165], v[10:11], v[140:141], v[114:115]
	v_and_b32_e32 v117, 0xffff0000, v41
	v_pk_mul_f32 v[140:141], v[164:165], v[148:149]
	v_pk_mul_f32 v[150:151], v[154:155], v[154:155]
	v_fma_f32 v33, v22, v140, 0
	v_fmac_f32_e32 v33, v23, v141
	v_lshlrev_b32_e32 v140, 16, v35
	v_and_b32_e32 v141, 0xffff0000, v35
	v_pk_add_f32 v[140:141], v[140:141], v[116:117] neg_lo:[0,1] neg_hi:[0,1]
	v_add_f32_e32 v28, v150, v151
	v_pk_fma_f32 v[140:141], v[4:5], v[140:141], v[116:117]
	v_pk_mul_f32 v[142:143], v[154:155], v[142:143]
	v_pk_mul_f32 v[158:159], v[16:17], v[140:141]
	v_pk_mul_f32 v[160:161], v[158:159], v[158:159]
	v_add_f32_e32 v28, v160, v28
	v_add_f32_e32 v28, v161, v28
	v_lshlrev_b32_e32 v156, 16, v49
	s_nop 0
	v_add_f32_dpp v28, v28, v28 row_ror:1 row_mask:0xf bank_mask:0xf bound_ctrl:1
	v_and_b32_e32 v157, 0xffff0000, v49
	v_lshlrev_b32_e32 v112, 16, v37
	v_add_f32_dpp v28, v28, v28 row_ror:2 row_mask:0xf bank_mask:0xf bound_ctrl:1
	v_and_b32_e32 v113, 0xffff0000, v37
	v_pk_add_f32 v[162:163], v[156:157], -1.0 op_sel_hi:[1,0]
	v_add_f32_dpp v28, v28, v28 row_ror:4 row_mask:0xf bank_mask:0xf bound_ctrl:1
	v_pk_fma_f32 v[150:151], v[20:21], v[162:163], 1.0 op_sel_hi:[1,1,0]
	v_pk_mul_f32 v[164:165], v[164:165], 1.0 op_sel_hi:[1,0]
	v_add_f32_dpp v28, v28, v28 row_ror:8 row_mask:0xf bank_mask:0xf bound_ctrl:1
	v_max_f32_e32 v28, 0x179abe15, v28
	v_rsq_f32_e32 v28, v28
	v_pk_mul_f32 v[150:151], v[150:151], v[140:141]
	v_pk_mul_f32 v[140:141], v[158:159], v[156:157]
	v_pk_mul_f32 v[160:161], v[142:143], v[28:29] op_sel_hi:[1,0]
	v_lshlrev_b32_e32 v142, 16, v43
	v_and_b32_e32 v143, 0xffff0000, v43
	v_pk_add_f32 v[142:143], v[142:143], v[112:113] neg_lo:[0,1] neg_hi:[0,1]
	v_pk_mul_f32 v[162:163], v[140:141], v[28:29] op_sel_hi:[1,0]
	v_pk_fma_f32 v[166:167], v[12:13], v[142:143], v[112:113]
	v_pk_mul_f32 v[156:157], v[154:155], v[28:29] op_sel_hi:[1,0] neg_lo:[0,1] neg_hi:[0,1]
	v_pk_mul_f32 v[142:143], v[166:167], v[150:151]
	v_fmac_f32_e32 v33, v24, v142
	v_cvt_f32_f16_sdwa v155, v45 dst_sel:DWORD dst_unused:UNUSED_PAD src0_sel:WORD_1
	v_cvt_f32_f16_e32 v154, v45
	v_fmac_f32_e32 v33, v25, v143
	s_nop 1
	v_add_f32_dpp v33, v33, v33 row_ror:1 row_mask:0xf bank_mask:0xf bound_ctrl:1
	s_nop 1
	v_add_f32_dpp v33, v33, v33 row_ror:2 row_mask:0xf bank_mask:0xf bound_ctrl:1
	s_nop 1
	v_add_f32_dpp v33, v33, v33 row_ror:4 row_mask:0xf bank_mask:0xf bound_ctrl:1
	v_mov_b32_e32 v81, 0
	v_pk_add_f32 v[154:155], v[154:155], 1.0 op_sel_hi:[1,0] neg_lo:[1,0] neg_hi:[1,0]
	s_nop 0
	v_mov_b32_dpp v81, v33 row_ror:8 row_mask:0xf bank_mask:0xf
	v_pk_mul_f32 v[158:159], v[158:159], v[28:29] op_sel_hi:[1,0] neg_lo:[0,1] neg_hi:[0,1]
	v_pk_mul_f32 v[166:167], v[166:167], 1.0 op_sel_hi:[1,0]
	v_pk_mov_b32 v[174:175], v[152:153], v[152:153] op_sel:[0,1]
	v_pk_mov_b32 v[176:177], v[154:155], v[154:155] op_sel:[0,1]
	v_pk_mov_b32 v[178:179], v[148:149], v[148:149] op_sel:[0,1]
	v_pk_mov_b32 v[180:181], v[150:151], v[150:151] op_sel:[0,1]
	v_pk_mov_b32 v[182:183], v[156:157], v[156:157] op_sel:[0,1]
	v_pk_mov_b32 v[184:185], v[158:159], v[158:159] op_sel:[0,1]
	v_pk_mov_b32 v[186:187], v[160:161], v[160:161] op_sel:[0,1]
	v_pk_mov_b32 v[188:189], v[162:163], v[162:163] op_sel:[0,1]
	v_pk_mov_b32 v[190:191], v[164:165], v[164:165] op_sel:[0,1]
	v_pk_mov_b32 v[192:193], v[166:167], v[166:167] op_sel:[0,1]
	v_mov_b32_e32 v194, v127
	ds_write_b128 v127, v[144:147] offset:51456
	s_and_saveexec_b64 s[52:53], s[4:5]
	s_or_b64 exec, exec, s[52:53]
	s_waitcnt vmcnt(17)
	v_lshlrev_b32_e32 v140, 16, v50
	v_and_b32_e32 v141, 0xffff0000, v50
	s_waitcnt vmcnt(2)
	v_lshlrev_b32_e32 v142, 16, v58
	v_and_b32_e32 v143, 0xffff0000, v58
	v_pk_add_f32 v[118:119], v[118:119], v[140:141] neg_lo:[0,1] neg_hi:[0,1]
	v_lshlrev_b32_e32 v150, 16, v59
	v_pk_fma_f32 v[118:119], v[2:3], v[118:119], v[140:141]
	v_pk_add_f32 v[140:141], v[142:143], -1.0 op_sel_hi:[1,0]
	v_pk_mul_f32 v[146:147], v[14:15], v[118:119]
	v_pk_fma_f32 v[140:141], v[18:19], v[140:141], 1.0 op_sel_hi:[1,1,0]
	v_pk_mul_f32 v[152:153], v[146:147], v[142:143]
	v_pk_mul_f32 v[140:141], v[140:141], v[118:119]
	v_cvt_f32_f16_sdwa v119, v52 dst_sel:DWORD dst_unused:UNUSED_PAD src0_sel:WORD_1
	v_cvt_f32_f16_e32 v118, v52
	s_waitcnt vmcnt(6)
; #define LAS __attribute__((address_space(3)))
; __device__ __forceinline__ float scan_prepare(const ScanRegs& R, const u32x2 qr_, const u32x2 qk_, const u32x2 qv_, LAS float* slot, int cq, const f32x4 mur, const f32x4 muk, const f32x4 muv, const f32x4 kkc, const f32x4 kac, const f32x4 rkc) {
;     float pr[4], pk[4], pv[4], qr[4], qk[4], qv[4], av[4], om[4];
;     unpack4(R.pr, pr); unpack4(R.pk, pk); unpack4(R.pv, pv); unpack4(qr_, qr); unpack4(qk_, qk); unpack4(qv_, qv); unpack4(R.as, av);
;     om[0] = f16_to_f((unsigned short)(R.wl.x & 0xffffu)); om[1] = f16_to_f((unsigned short)(R.wl.x >> 16)); om[2] = f16_to_f((unsigned short)(R.wl.y & 0xffffu)); om[3] = f16_to_f((unsigned short)(R.wl.y >> 16));
;     float rr[4], vv[4], kn[4], k2[4], dec[4], bu[4];
;     float ssq = 0.f, bon = 0.f, c1 = 0.f, c2 = 0.f;
; #pragma unroll
;     for (int j = 0; j < 4; ++j) {
;         rr[j] = pr[j] + (qr[j] - pr[j]) * mur[j]; const float kk0 = pk[j] + (qk[j] - pk[j]) * muk[j]; vv[j] = pv[j] + (qv[j] - pv[j]) * muv[j];
;         dec[j] = 1.0f - om[j];
;         kn[j] = kk0 * kkc[j]; ssq += kn[j] * kn[j];
;         k2[j] = kk0 * (1.0f + (av[j] - 1.0f) * kac[j]);
;         const float t = rr[j] * k2[j]; bon += t * rkc[j]; c2 += t;
;         bu[j] = kn[j] * av[j]; c1 += bu[j] * rr[j];
;     }
;     ssq += dpp_f<0x121>(ssq); bon += dpp_f<0x121>(bon); c1 += dpp_f<0x121>(c1); c2 += dpp_f<0x121>(c2);
;     ssq += dpp_f<0x122>(ssq); bon += dpp_f<0x122>(bon); c1 += dpp_f<0x122>(c1); c2 += dpp_f<0x122>(c2);
;     ssq += dpp_f<0x124>(ssq); bon += dpp_f<0x124>(bon); c1 += dpp_f<0x124>(c1); c2 += dpp_f<0x124>(c2);
;     ssq += dpp_f<0x128>(ssq); bon += dpp_f<0x128>(bon); c1 += dpp_f<0x128>(c1); c2 += dpp_f<0x128>(c2);
;     const float inv = __builtin_amdgcn_rsqf(fmaxf(ssq, 1e-24f));
;     f32x4 o_al, o_be, o_wr;
; #pragma unroll
;     for (int j = 0; j < 4; ++j) { o_al[j] = -(kn[j] * inv); o_be[j] = bu[j] * inv; o_wr[j] = dec[j] * rr[j]; }
;     LAS f32x4* s4 = (LAS f32x4*)slot;
;     s4[cq] = (f32x4){dec[0], dec[1], dec[2], dec[3]}; s4[16 + cq] = (f32x4){k2[0], k2[1], k2[2], k2[3]}; s4[32 + cq] = o_al; s4[48 + cq] = o_be; s4[64 + cq] = o_wr;
;     s4[80 + cq] = (f32x4){vv[0], vv[1], vv[2], vv[3]};
;     if (cq == 0) *(LAS f32x2*)(slot + 384) = (f32x2){c1 * inv, c2};
;     return bon;
; }
	v_lshlrev_b32_e32 v142, 16, v82
	v_and_b32_e32 v143, 0xffff0000, v82
	v_pk_add_f32 v[114:115], v[114:115], v[142:143] neg_lo:[0,1] neg_hi:[0,1]
	v_pk_add_f32 v[144:145], v[118:119], 1.0 op_sel_hi:[1,0] neg_lo:[1,0] neg_hi:[1,0]
	v_pk_fma_f32 v[118:119], v[10:11], v[114:115], v[142:143]
	v_pk_mul_f32 v[148:149], v[146:147], v[146:147]
	v_pk_mul_f32 v[114:115], v[118:119], v[140:141]
	v_fma_f32 v156, v22, v114, 0
	v_fmac_f32_e32 v156, v23, v115
	v_lshlrev_b32_e32 v114, 16, v51
	v_and_b32_e32 v115, 0xffff0000, v51
	v_pk_add_f32 v[116:117], v[116:117], v[114:115] neg_lo:[0,1] neg_hi:[0,1]
	v_add_f32_e32 v28, v148, v149
	v_pk_fma_f32 v[114:115], v[4:5], v[116:117], v[114:115]
	v_and_b32_e32 v151, 0xffff0000, v59
	v_pk_mul_f32 v[116:117], v[16:17], v[114:115]
	v_pk_add_f32 v[154:155], v[150:151], -1.0 op_sel_hi:[1,0]
	v_pk_mul_f32 v[142:143], v[116:117], v[116:117]
	s_waitcnt vmcnt(5)
	v_lshlrev_b32_e32 v160, 16, v88
	v_add_f32_e32 v28, v142, v28
	v_add_f32_e32 v28, v143, v28
	v_pk_fma_f32 v[142:143], v[20:21], v[154:155], 1.0 op_sel_hi:[1,1,0]
	v_and_b32_e32 v161, 0xffff0000, v88
	v_add_f32_dpp v28, v28, v28 row_ror:1 row_mask:0xf bank_mask:0xf bound_ctrl:1
	v_pk_mul_f32 v[142:143], v[142:143], v[114:115]
	v_pk_mul_f32 v[114:115], v[116:117], v[150:151]
	v_add_f32_dpp v28, v28, v28 row_ror:2 row_mask:0xf bank_mask:0xf bound_ctrl:1
	v_lshlrev_b32_e32 v162, 16, v89
	v_and_b32_e32 v163, 0xffff0000, v89
	v_add_f32_dpp v28, v28, v28 row_ror:4 row_mask:0xf bank_mask:0xf bound_ctrl:1
	v_pk_add_f32 v[108:109], v[108:109], v[160:161] neg_lo:[0,1] neg_hi:[0,1]
	v_pk_add_f32 v[110:111], v[110:111], v[162:163] neg_lo:[0,1] neg_hi:[0,1]
	v_add_f32_dpp v28, v28, v28 row_ror:8 row_mask:0xf bank_mask:0xf bound_ctrl:1
	v_max_f32_e32 v28, 0x179abe15, v28
	v_rsq_f32_e32 v28, v28
	v_pk_fma_f32 v[110:111], v[8:9], v[110:111], v[162:163]
	v_pk_fma_f32 v[108:109], v[6:7], v[108:109], v[160:161]
	v_pk_mul_f32 v[150:151], v[116:117], v[28:29] op_sel_hi:[1,0] neg_lo:[0,1] neg_hi:[0,1]
	v_lshlrev_b32_e32 v116, 16, v83
	v_and_b32_e32 v117, 0xffff0000, v83
	v_pk_add_f32 v[112:113], v[112:113], v[116:117] neg_lo:[0,1] neg_hi:[0,1]
	v_pk_mul_f32 v[154:155], v[114:115], v[28:29] op_sel_hi:[1,0]
	v_pk_fma_f32 v[158:159], v[12:13], v[112:113], v[116:117]
	v_pk_mul_f32 v[148:149], v[146:147], v[28:29] op_sel_hi:[1,0] neg_lo:[0,1] neg_hi:[0,1]
	v_pk_mul_f32 v[112:113], v[158:159], v[142:143]
	v_fmac_f32_e32 v156, v24, v112
	v_cvt_f32_f16_sdwa v147, v53 dst_sel:DWORD dst_unused:UNUSED_PAD src0_sel:WORD_1
	v_cvt_f32_f16_e32 v146, v53
	v_fmac_f32_e32 v156, v25, v113
	s_nop 1
	v_add_f32_dpp v114, v156, v156 row_ror:1 row_mask:0xf bank_mask:0xf bound_ctrl:1
	s_nop 1
	v_add_f32_dpp v114, v114, v114 row_ror:2 row_mask:0xf bank_mask:0xf bound_ctrl:1
	s_nop 1
	v_add_f32_dpp v112, v114, v114 row_ror:4 row_mask:0xf bank_mask:0xf bound_ctrl:1
	v_mov_b32_e32 v113, 0
	v_pk_add_f32 v[146:147], v[146:147], 1.0 op_sel_hi:[1,0] neg_lo:[1,0] neg_hi:[1,0]
	s_nop 0
	v_mov_b32_dpp v113, v112 row_ror:8 row_mask:0xf bank_mask:0xf
	v_pk_mul_f32 v[152:153], v[152:153], v[28:29] op_sel_hi:[1,0]
	v_pk_mul_f32 v[156:157], v[118:119], 1.0 op_sel_hi:[1,0]
	v_pk_mul_f32 v[158:159], v[158:159], 1.0 op_sel_hi:[1,0]
	ds_write_b128 v129, v[108:111] offset:51456
	v_pk_mul_f32 v[196:197], v[174:175], v[144:145]
	v_pk_mul_f32 v[198:199], v[176:177], v[146:147]
	v_mov_b32_e32 v200, v196
	v_mov_b32_e32 v201, v197
	v_mov_b32_e32 v202, v198
	v_mov_b32_e32 v203, v199
	v_mov_b32_e32 v208, v196
	v_mov_b32_e32 v209, v197
	v_mov_b32_e32 v210, v198
	v_mov_b32_e32 v211, v199
	v_permlane16_swap_b32 v200, v208
	v_permlane16_swap_b32 v201, v209
	v_permlane16_swap_b32 v202, v210
	v_permlane16_swap_b32 v203, v211
	v_pk_mul_f32 v[204:205], v[200:201], v[208:209]
	v_pk_mul_f32 v[206:207], v[202:203], v[210:211]
	v_mov_b32_e32 v208, v204
	v_mov_b32_e32 v209, v205
	v_mov_b32_e32 v210, v206
	v_mov_b32_e32 v211, v207
	v_permlane32_swap_b32 v204, v208
	v_permlane32_swap_b32 v205, v209
	v_permlane32_swap_b32 v206, v210
	v_permlane32_swap_b32 v207, v211
	v_fma_f32 v200, v200, v235, v236
	v_fma_f32 v201, v201, v235, v236
	v_fma_f32 v202, v202, v235, v236
	v_fma_f32 v203, v203, v235, v236
	v_fma_f32 v208, v204, v237, v238
	v_fma_f32 v209, v205, v237, v238
	v_fma_f32 v210, v206, v237, v238
	v_fma_f32 v211, v207, v237, v238
	v_pk_mul_f32 v[212:213], v[200:201], v[208:209]
	v_pk_mul_f32 v[214:215], v[202:203], v[210:211]
	v_pk_mul_f32 v[216:217], v[212:213], v[174:175]
	v_pk_mul_f32 v[218:219], v[214:215], v[176:177]
	v_pk_mul_f32 v[220:221], v[216:217], v[144:145]
	v_pk_mul_f32 v[222:223], v[218:219], v[146:147]
	v_rcp_f32_e32 v224, v216
	v_rcp_f32_e32 v225, v217
	v_rcp_f32_e32 v226, v218
	v_rcp_f32_e32 v227, v219
	v_rcp_f32_e32 v228, v220
	v_rcp_f32_e32 v229, v221
	v_rcp_f32_e32 v230, v222
	v_rcp_f32_e32 v231, v223
	s_nop 0
	v_pk_mul_f32 v[182:183], v[182:183], v[212:213]
	v_pk_mul_f32 v[184:185], v[184:185], v[214:215]
	v_pk_mul_f32 v[178:179], v[178:179], v[224:225]
	v_pk_mul_f32 v[180:181], v[180:181], v[226:227]
	ds_write_b128 v194, v[178:181] offset:50432
	v_pk_mul_f32 v[186:187], v[186:187], v[224:225]
	v_pk_mul_f32 v[188:189], v[188:189], v[226:227]
	ds_write_b128 v194, v[182:185] offset:50688
	v_pk_mul_f32 v[190:191], v[190:191], v[216:217]
	v_pk_mul_f32 v[192:193], v[192:193], v[218:219]
	ds_write_b128 v194, v[186:189] offset:50944
	v_pk_mul_f32 v[240:241], v[140:141], v[228:229]
	v_pk_mul_f32 v[242:243], v[142:143], v[230:231]
	ds_write_b128 v194, v[190:193] offset:51200
	v_pk_mul_f32 v[244:245], v[148:149], v[216:217]
	v_pk_mul_f32 v[246:247], v[150:151], v[218:219]
	ds_write_b128 v129, v[220:223] offset:50176
	v_pk_mul_f32 v[196:197], v[152:153], v[228:229]
	v_pk_mul_f32 v[198:199], v[154:155], v[230:231]
	ds_write_b128 v129, v[240:243] offset:50432
	v_pk_mul_f32 v[200:201], v[156:157], v[220:221]
	v_pk_mul_f32 v[202:203], v[158:159], v[222:223]
	ds_write_b128 v129, v[244:247] offset:50688
	ds_write_b128 v129, v[196:199] offset:50944
	ds_write_b128 v129, v[200:203] offset:51200
	s_and_saveexec_b64 s[52:53], s[4:5]
	s_cbranch_execz .LBB0_1121
	s_or_b64 exec, exec, s[52:53]
	s_and_saveexec_b64 s[52:53], s[44:45]
	s_cbranch_execnz .LBB0_1122

; #define LAS __attribute__((address_space(3)))
; __device__ __forceinline__ float f16_to_f(unsigned short h) { return (float)__builtin_bit_cast(_Float16, h); }
; template <int CTRL> __device__ __forceinline__ float dpp_f(float x) { return __int_as_float(__builtin_amdgcn_update_dpp(0, __float_as_int(x), CTRL, 0xf, 0xf, false)); }
; __device__ __forceinline__ void unpack4(const u32x2 u, float (&f)[4]) { f[0] = lo_bf(u.x); f[1] = hi_bf(u.x); f[2] = lo_bf(u.y); f[3] = hi_bf(u.y); }
; __device__ __forceinline__ float scan_prepare(const ScanRegs& R, const u32x2 qr_, const u32x2 qk_, const u32x2 qv_, LAS float* slot, int cq, const f32x4 mur, const f32x4 muk, const f32x4 muv, const f32x4 kkc, const f32x4 kac, const f32x4 rkc) {
;     float pr[4], pk[4], pv[4], qr[4], qk[4], qv[4], av[4], om[4];
;     unpack4(R.pr, pr); unpack4(R.pk, pk); unpack4(R.pv, pv); unpack4(qr_, qr); unpack4(qk_, qk); unpack4(qv_, qv); unpack4(R.as, av);
;     om[0] = f16_to_f((unsigned short)(R.wl.x & 0xffffu)); om[1] = f16_to_f((unsigned short)(R.wl.x >> 16)); om[2] = f16_to_f((unsigned short)(R.wl.y & 0xffffu)); om[3] = f16_to_f((unsigned short)(R.wl.y >> 16));
;     float rr[4], vv[4], kn[4], k2[4], dec[4], bu[4];
;     float ssq = 0.f, bon = 0.f, c1 = 0.f, c2 = 0.f;
; #pragma unroll
;     for (int j = 0; j < 4; ++j) {
;         rr[j] = pr[j] + (qr[j] - pr[j]) * mur[j]; const float kk0 = pk[j] + (qk[j] - pk[j]) * muk[j]; vv[j] = pv[j] + (qv[j] - pv[j]) * muv[j];
;         dec[j] = 1.0f - om[j];
;         kn[j] = kk0 * kkc[j]; ssq += kn[j] * kn[j];
;         k2[j] = kk0 * (1.0f + (av[j] - 1.0f) * kac[j]);
;         const float t = rr[j] * k2[j]; bon += t * rkc[j]; c2 += t;
;         bu[j] = kn[j] * av[j]; c1 += bu[j] * rr[j];
;     }
;     ssq += dpp_f<0x121>(ssq); bon += dpp_f<0x121>(bon); c1 += dpp_f<0x121>(c1); c2 += dpp_f<0x121>(c2);
.LBB0_1114:
	v_lshl_add_u64 v[48:49], s[92:93], 0, v[66:67]
	v_add_co_u32_e32 v40, vcc, 0x7200000, v48
	v_lshl_add_u64 v[38:39], s[92:93], 0, v[60:61]
	s_nop 0
	v_addc_co_u32_e32 v41, vcc, 0, v49, vcc
	v_add_co_u32_e32 v50, vcc, 0x7201000, v48
	v_lshl_add_u64 v[58:59], s[90:91], 0, v[60:61]
	s_nop 0
	v_addc_co_u32_e32 v51, vcc, 0, v49, vcc
	v_add_co_u32_e32 v34, vcc, 0x71fe000, v48
	s_nop 1
	v_addc_co_u32_e32 v35, vcc, 0, v49, vcc
	v_add_co_u32_e32 v36, vcc, 0x71ff000, v48
	s_nop 1
	v_addc_co_u32_e32 v37, vcc, 0, v49, vcc
	v_add_co_u32_e32 v52, vcc, 0x17a00000, v38
	s_nop 1
	v_addc_co_u32_e32 v53, vcc, 0, v39, vcc
	v_add_co_u32_e32 v48, vcc, 0x7202000, v48
	global_load_dwordx2 v[42:43], v[34:35], off offset:2048
	s_nop 0
	global_load_dwordx2 v[34:35], v[36:37], off
	global_load_dwordx2 v[38:39], v[36:37], off offset:2048
	global_load_dwordx2 v[44:45], v[52:53], off
	v_addc_co_u32_e32 v49, vcc, 0, v49, vcc
	global_load_dwordx2 v[36:37], v[40:41], off
	s_nop 0
	global_load_dwordx2 v[40:41], v[40:41], off offset:2048
	s_nop 0
	global_load_dwordx2 v[46:47], v[50:51], off
	global_load_dwordx2 v[82:83], v[50:51], off offset:2048
	s_nop 0
	global_load_dwordx2 v[50:51], v[48:49], off
	global_load_dwordx2 v[88:89], v[48:49], off offset:2048
	s_nop 0
	global_load_dwordx2 v[52:53], v[52:53], off offset:2048
	s_nop 0
	global_load_dwordx2 v[48:49], v[58:59], off
	s_nop 0
	global_load_dwordx2 v[58:59], v[58:59], off offset:2048
.LBB0_1115:
	s_cmp_eq_u32 s14, 0
	s_cbranch_scc1 .Lyblk_skip
	v_add_u32_e32 v33, v93, v130
	ds_read_b128 v[108:111], v33
	v_add_u32_e32 v28, s73, v139
	v_lshlrev_b64 v[112:113], 11, v[28:29]
	v_add_u32_e32 v28, v93, v131
	v_lshl_add_u64 v[116:117], v[90:91], 0, v[112:113]
	ds_read_b128 v[112:115], v28
	s_waitcnt lgkmcnt(1)
	v_add_f32_e32 v28, v108, v109
	v_add_f32_e32 v33, v110, v111
	v_add_f32_e32 v28, v28, v33
	v_bfe_u32 v33, v28, 16, 1
	v_add3_u32 v28, v28, v33, s67
	global_store_short_d16_hi v[116:117], v28, off
	s_waitcnt lgkmcnt(0)
	v_add_f32_e32 v28, v112, v113
	v_add_f32_e32 v33, v114, v115
	v_add_f32_e32 v28, v28, v33
	v_bfe_u32 v33, v28, 16, 1
	v_add3_u32 v28, v28, v33, s67
	global_store_short_d16_hi v[116:117], v28, off offset:2048
.Lyblk_skip:
	v_add_u32_e32 v28, v120, v130
	s_waitcnt lgkmcnt(0)
	s_barrier
	ds_read_b128 v[108:111], v28
	v_lshl_add_u64 v[112:113], s[92:93], 0, v[100:101]
	v_add_co_u32_e32 v112, vcc, s68, v112
	s_cmpk_gt_u32 s14, 0xfd
	s_waitcnt lgkmcnt(0)
	v_add_f32_e32 v28, v108, v109
	v_add_f32_e32 v33, v110, v111
	v_add_f32_e32 v28, v28, v33
	v_bfe_u32 v33, v28, 16, 1
	v_add3_u32 v28, v28, v33, s67
	v_addc_co_u32_e32 v113, vcc, 0, v113, vcc
	global_store_short_d16_hi v[112:113], v28, off
	v_add_u32_e32 v28, v120, v131
	ds_read_b128 v[108:111], v28
	s_cselect_b64 s[52:53], -1, 0
	s_and_b64 vcc, exec, s[52:53]
	s_waitcnt lgkmcnt(0)
	v_add_f32_e32 v28, v108, v109
	v_add_f32_e32 v33, v110, v111
	v_add_f32_e32 v28, v28, v33
	v_bfe_u32 v33, v28, 16, 1
	v_add3_u32 v28, v28, v33, s67
	global_store_short_d16_hi v[112:113], v28, off offset:2048
	s_cbranch_vccnz .LBB0_1106
	v_lshlrev_b32_e32 v108, 16, v76
	v_and_b32_e32 v109, 0xffff0000, v76
	v_lshlrev_b32_e32 v110, 16, v62
	v_and_b32_e32 v111, 0xffff0000, v62
	v_pk_add_f32 v[110:111], v[110:111], v[108:109] neg_lo:[0,1] neg_hi:[0,1]
	v_lshlrev_b32_e32 v140, 16, v63
	v_pk_fma_f32 v[144:145], v[6:7], v[110:111], v[108:109]
	v_lshlrev_b32_e32 v110, 16, v77
	v_and_b32_e32 v111, 0xffff0000, v77
	v_and_b32_e32 v141, 0xffff0000, v63
	v_pk_add_f32 v[140:141], v[140:141], v[110:111] neg_lo:[0,1] neg_hi:[0,1]
	v_lshlrev_b32_e32 v118, 16, v64
	v_and_b32_e32 v119, 0xffff0000, v64
	v_pk_fma_f32 v[146:147], v[8:9], v[140:141], v[110:111]
	v_lshlrev_b32_e32 v140, 16, v54
	v_and_b32_e32 v141, 0xffff0000, v54
	s_waitcnt vmcnt(3)
	v_lshlrev_b32_e32 v142, 16, v86
	v_and_b32_e32 v143, 0xffff0000, v86
	v_pk_add_f32 v[140:141], v[140:141], v[118:119] neg_lo:[0,1] neg_hi:[0,1]
	v_pk_add_f32 v[148:149], v[142:143], -1.0 op_sel_hi:[1,0]
	v_pk_fma_f32 v[140:141], v[2:3], v[140:141], v[118:119]
	v_pk_fma_f32 v[148:149], v[18:19], v[148:149], 1.0 op_sel_hi:[1,1,0]
	v_pk_mul_f32 v[154:155], v[14:15], v[140:141]
	v_pk_mul_f32 v[148:149], v[140:141], v[148:149]
	v_cvt_f32_f16_sdwa v141, v72 dst_sel:DWORD dst_unused:UNUSED_PAD src0_sel:WORD_1
	v_cvt_f32_f16_e32 v140, v72
	v_lshlrev_b32_e32 v114, 16, v56
	v_and_b32_e32 v115, 0xffff0000, v56
	v_lshlrev_b32_e32 v156, 16, v68
	v_and_b32_e32 v157, 0xffff0000, v68
	v_pk_add_f32 v[152:153], v[140:141], 1.0 op_sel_hi:[1,0] neg_lo:[1,0] neg_hi:[1,0]
	v_pk_add_f32 v[140:141], v[156:157], v[114:115] neg_lo:[0,1] neg_hi:[0,1]
	v_lshlrev_b32_e32 v116, 16, v65
	v_pk_fma_f32 v[164:165], v[10:11], v[140:141], v[114:115]
	v_and_b32_e32 v117, 0xffff0000, v65
	v_pk_mul_f32 v[140:141], v[164:165], v[148:149]
	v_pk_mul_f32 v[150:151], v[154:155], v[154:155]
	v_fma_f32 v33, v22, v140, 0
	v_fmac_f32_e32 v33, v23, v141
	v_lshlrev_b32_e32 v140, 16, v55
	v_and_b32_e32 v141, 0xffff0000, v55
	v_pk_add_f32 v[140:141], v[140:141], v[116:117] neg_lo:[0,1] neg_hi:[0,1]
	v_add_f32_e32 v28, v150, v151
	v_pk_fma_f32 v[140:141], v[4:5], v[140:141], v[116:117]
	v_pk_mul_f32 v[142:143], v[154:155], v[142:143]
	v_pk_mul_f32 v[158:159], v[16:17], v[140:141]
	v_pk_mul_f32 v[160:161], v[158:159], v[158:159]
	v_add_f32_e32 v28, v160, v28
	v_add_f32_e32 v28, v161, v28
	v_lshlrev_b32_e32 v156, 16, v87
	s_nop 0
	v_add_f32_dpp v28, v28, v28 row_ror:1 row_mask:0xf bank_mask:0xf bound_ctrl:1
	v_and_b32_e32 v157, 0xffff0000, v87
	v_lshlrev_b32_e32 v112, 16, v57
	v_add_f32_dpp v28, v28, v28 row_ror:2 row_mask:0xf bank_mask:0xf bound_ctrl:1
	v_and_b32_e32 v113, 0xffff0000, v57
; #define LAS __attribute__((address_space(3)))
; template <int CTRL> __device__ __forceinline__ float dpp_f(float x) { return __int_as_float(__builtin_amdgcn_update_dpp(0, __float_as_int(x), CTRL, 0xf, 0xf, false)); }
; __device__ __forceinline__ float scan_prepare(const ScanRegs& R, const u32x2 qr_, const u32x2 qk_, const u32x2 qv_, LAS float* slot, int cq, const f32x4 mur, const f32x4 muk, const f32x4 muv, const f32x4 kkc, const f32x4 kac, const f32x4 rkc) {
;     ...
;     ssq += dpp_f<0x121>(ssq); bon += dpp_f<0x121>(bon); c1 += dpp_f<0x121>(c1); c2 += dpp_f<0x121>(c2);
;     ssq += dpp_f<0x122>(ssq); bon += dpp_f<0x122>(bon); c1 += dpp_f<0x122>(c1); c2 += dpp_f<0x122>(c2);
;     ssq += dpp_f<0x124>(ssq); bon += dpp_f<0x124>(bon); c1 += dpp_f<0x124>(c1); c2 += dpp_f<0x124>(c2);
;     ssq += dpp_f<0x128>(ssq); bon += dpp_f<0x128>(bon); c1 += dpp_f<0x128>(c1); c2 += dpp_f<0x128>(c2);
;     const float inv = __builtin_amdgcn_rsqf(fmaxf(ssq, 1e-24f));
;     f32x4 o_al, o_be, o_wr;
; #pragma unroll
;     for (int j = 0; j < 4; ++j) { o_al[j] = -(kn[j] * inv); o_be[j] = bu[j] * inv; o_wr[j] = dec[j] * rr[j]; }
;     LAS f32x4* s4 = (LAS f32x4*)slot;
;     s4[cq] = (f32x4){dec[0], dec[1], dec[2], dec[3]}; s4[16 + cq] = (f32x4){k2[0], k2[1], k2[2], k2[3]}; s4[32 + cq] = o_al; s4[48 + cq] = o_be; s4[64 + cq] = o_wr;
;     s4[80 + cq] = (f32x4){vv[0], vv[1], vv[2], vv[3]};
;     if (cq == 0) *(LAS f32x2*)(slot + 384) = (f32x2){c1 * inv, c2};
	v_pk_add_f32 v[162:163], v[156:157], -1.0 op_sel_hi:[1,0]
	v_add_f32_dpp v28, v28, v28 row_ror:4 row_mask:0xf bank_mask:0xf bound_ctrl:1
	v_pk_fma_f32 v[150:151], v[20:21], v[162:163], 1.0 op_sel_hi:[1,1,0]
	v_pk_mul_f32 v[164:165], v[164:165], 1.0 op_sel_hi:[1,0]
	v_add_f32_dpp v28, v28, v28 row_ror:8 row_mask:0xf bank_mask:0xf bound_ctrl:1
	v_max_f32_e32 v28, 0x179abe15, v28
	v_rsq_f32_e32 v28, v28
	v_pk_mul_f32 v[150:151], v[140:141], v[150:151]
	v_pk_mul_f32 v[140:141], v[158:159], v[156:157]
	v_pk_mul_f32 v[160:161], v[142:143], v[28:29] op_sel_hi:[1,0]
	v_lshlrev_b32_e32 v142, 16, v69
	v_and_b32_e32 v143, 0xffff0000, v69
	v_pk_add_f32 v[142:143], v[142:143], v[112:113] neg_lo:[0,1] neg_hi:[0,1]
	v_pk_mul_f32 v[162:163], v[140:141], v[28:29] op_sel_hi:[1,0]
	v_pk_fma_f32 v[166:167], v[12:13], v[142:143], v[112:113]
	v_pk_mul_f32 v[156:157], v[154:155], v[28:29] op_sel_hi:[1,0] neg_lo:[0,1] neg_hi:[0,1]
	v_pk_mul_f32 v[142:143], v[166:167], v[150:151]
	v_fmac_f32_e32 v33, v24, v142
	v_cvt_f32_f16_sdwa v155, v73 dst_sel:DWORD dst_unused:UNUSED_PAD src0_sel:WORD_1
	v_cvt_f32_f16_e32 v154, v73
	v_fmac_f32_e32 v33, v25, v143
	s_nop 1
	v_add_f32_dpp v33, v33, v33 row_ror:1 row_mask:0xf bank_mask:0xf bound_ctrl:1
	s_nop 1
	v_add_f32_dpp v33, v33, v33 row_ror:2 row_mask:0xf bank_mask:0xf bound_ctrl:1
	s_nop 1
	v_add_f32_dpp v33, v33, v33 row_ror:4 row_mask:0xf bank_mask:0xf bound_ctrl:1
	v_mov_b32_e32 v81, 0
	v_pk_add_f32 v[154:155], v[154:155], 1.0 op_sel_hi:[1,0] neg_lo:[1,0] neg_hi:[1,0]
	s_nop 0
	v_mov_b32_dpp v81, v33 row_ror:8 row_mask:0xf bank_mask:0xf
	v_pk_mul_f32 v[158:159], v[158:159], v[28:29] op_sel_hi:[1,0] neg_lo:[0,1] neg_hi:[0,1]
	v_pk_mul_f32 v[166:167], v[166:167], 1.0 op_sel_hi:[1,0]
	v_pk_mov_b32 v[174:175], v[152:153], v[152:153] op_sel:[0,1]
	v_pk_mov_b32 v[176:177], v[154:155], v[154:155] op_sel:[0,1]
	v_pk_mov_b32 v[178:179], v[148:149], v[148:149] op_sel:[0,1]
	v_pk_mov_b32 v[180:181], v[150:151], v[150:151] op_sel:[0,1]
	v_pk_mov_b32 v[182:183], v[156:157], v[156:157] op_sel:[0,1]
	v_pk_mov_b32 v[184:185], v[158:159], v[158:159] op_sel:[0,1]
	v_pk_mov_b32 v[186:187], v[160:161], v[160:161] op_sel:[0,1]
	v_pk_mov_b32 v[188:189], v[162:163], v[162:163] op_sel:[0,1]
	v_pk_mov_b32 v[190:191], v[164:165], v[164:165] op_sel:[0,1]
	v_pk_mov_b32 v[192:193], v[166:167], v[166:167] op_sel:[0,1]
	v_mov_b32_e32 v194, v127
	ds_write_b128 v127, v[144:147] offset:1280
	s_and_saveexec_b64 s[56:57], s[4:5]
	s_or_b64 exec, exec, s[56:57]
	s_waitcnt vmcnt(4)
	v_lshlrev_b32_e32 v140, 16, v96
	v_and_b32_e32 v141, 0xffff0000, v96
	s_waitcnt vmcnt(2)
; #define LAS __attribute__((address_space(3)))
; __device__ __forceinline__ float scan_prepare(const ScanRegs& R, const u32x2 qr_, const u32x2 qk_, const u32x2 qv_, LAS float* slot, int cq, const f32x4 mur, const f32x4 muk, const f32x4 muv, const f32x4 kkc, const f32x4 kac, const f32x4 rkc) {
;     float pr[4], pk[4], pv[4], qr[4], qk[4], qv[4], av[4], om[4];
;     unpack4(R.pr, pr); unpack4(R.pk, pk); unpack4(R.pv, pv); unpack4(qr_, qr); unpack4(qk_, qk); unpack4(qv_, qv); unpack4(R.as, av);
;     om[0] = f16_to_f((unsigned short)(R.wl.x & 0xffffu)); om[1] = f16_to_f((unsigned short)(R.wl.x >> 16)); om[2] = f16_to_f((unsigned short)(R.wl.y & 0xffffu)); om[3] = f16_to_f((unsigned short)(R.wl.y >> 16));
;     float rr[4], vv[4], kn[4], k2[4], dec[4], bu[4];
;     float ssq = 0.f, bon = 0.f, c1 = 0.f, c2 = 0.f;
; #pragma unroll
;     for (int j = 0; j < 4; ++j) {
;         rr[j] = pr[j] + (qr[j] - pr[j]) * mur[j]; const float kk0 = pk[j] + (qk[j] - pk[j]) * muk[j]; vv[j] = pv[j] + (qv[j] - pv[j]) * muv[j];
;         dec[j] = 1.0f - om[j];
;         kn[j] = kk0 * kkc[j]; ssq += kn[j] * kn[j];
;         k2[j] = kk0 * (1.0f + (av[j] - 1.0f) * kac[j]);
;         const float t = rr[j] * k2[j]; bon += t * rkc[j]; c2 += t;
;         bu[j] = kn[j] * av[j]; c1 += bu[j] * rr[j];
;     }
;     ssq += dpp_f<0x121>(ssq); bon += dpp_f<0x121>(bon); c1 += dpp_f<0x121>(c1); c2 += dpp_f<0x121>(c2);
;     ssq += dpp_f<0x122>(ssq); bon += dpp_f<0x122>(bon); c1 += dpp_f<0x122>(c1); c2 += dpp_f<0x122>(c2);
;     ssq += dpp_f<0x124>(ssq); bon += dpp_f<0x124>(bon); c1 += dpp_f<0x124>(c1); c2 += dpp_f<0x124>(c2);
;     ssq += dpp_f<0x128>(ssq); bon += dpp_f<0x128>(bon); c1 += dpp_f<0x128>(c1); c2 += dpp_f<0x128>(c2);
;     const float inv = __builtin_amdgcn_rsqf(fmaxf(ssq, 1e-24f));
;     f32x4 o_al, o_be, o_wr;
; #pragma unroll
;     for (int j = 0; j < 4; ++j) { o_al[j] = -(kn[j] * inv); o_be[j] = bu[j] * inv; o_wr[j] = dec[j] * rr[j]; }
;     LAS f32x4* s4 = (LAS f32x4*)slot;
;     s4[cq] = (f32x4){dec[0], dec[1], dec[2], dec[3]}; s4[16 + cq] = (f32x4){k2[0], k2[1], k2[2], k2[3]}; s4[32 + cq] = o_al; s4[48 + cq] = o_be; s4[64 + cq] = o_wr;
;     s4[80 + cq] = (f32x4){vv[0], vv[1], vv[2], vv[3]};
;     if (cq == 0) *(LAS f32x2*)(slot + 384) = (f32x2){c1 * inv, c2};
;     return bon;
; }
	v_lshlrev_b32_e32 v142, 16, v102
	v_and_b32_e32 v143, 0xffff0000, v102
	v_pk_add_f32 v[118:119], v[118:119], v[140:141] neg_lo:[0,1] neg_hi:[0,1]
	v_lshlrev_b32_e32 v150, 16, v103
	v_pk_fma_f32 v[118:119], v[2:3], v[118:119], v[140:141]
	v_pk_add_f32 v[140:141], v[142:143], -1.0 op_sel_hi:[1,0]
	v_pk_mul_f32 v[146:147], v[14:15], v[118:119]
	v_pk_fma_f32 v[140:141], v[18:19], v[140:141], 1.0 op_sel_hi:[1,1,0]
	v_pk_mul_f32 v[152:153], v[146:147], v[142:143]
	v_pk_mul_f32 v[140:141], v[140:141], v[118:119]
	v_cvt_f32_f16_sdwa v119, v98 dst_sel:DWORD dst_unused:UNUSED_PAD src0_sel:WORD_1
	v_cvt_f32_f16_e32 v118, v98
	v_lshlrev_b32_e32 v142, 16, v84
	v_and_b32_e32 v143, 0xffff0000, v84
	v_pk_add_f32 v[114:115], v[114:115], v[142:143] neg_lo:[0,1] neg_hi:[0,1]
	v_pk_add_f32 v[144:145], v[118:119], 1.0 op_sel_hi:[1,0] neg_lo:[1,0] neg_hi:[1,0]
	v_pk_fma_f32 v[118:119], v[10:11], v[114:115], v[142:143]
	v_pk_mul_f32 v[148:149], v[146:147], v[146:147]
	v_pk_mul_f32 v[114:115], v[118:119], v[140:141]
	v_fma_f32 v156, v22, v114, 0
	v_fmac_f32_e32 v156, v23, v115
	v_lshlrev_b32_e32 v114, 16, v97
	v_and_b32_e32 v115, 0xffff0000, v97
	v_pk_add_f32 v[116:117], v[116:117], v[114:115] neg_lo:[0,1] neg_hi:[0,1]
	v_add_f32_e32 v28, v148, v149
	v_pk_fma_f32 v[114:115], v[4:5], v[116:117], v[114:115]
	v_and_b32_e32 v151, 0xffff0000, v103
	v_pk_mul_f32 v[116:117], v[16:17], v[114:115]
	v_pk_add_f32 v[154:155], v[150:151], -1.0 op_sel_hi:[1,0]
	v_pk_mul_f32 v[142:143], v[116:117], v[116:117]
	v_lshlrev_b32_e32 v160, 16, v94
	v_add_f32_e32 v28, v142, v28
	v_add_f32_e32 v28, v143, v28
	v_pk_fma_f32 v[142:143], v[20:21], v[154:155], 1.0 op_sel_hi:[1,1,0]
	v_and_b32_e32 v161, 0xffff0000, v94
	v_add_f32_dpp v28, v28, v28 row_ror:1 row_mask:0xf bank_mask:0xf bound_ctrl:1
	v_pk_mul_f32 v[142:143], v[142:143], v[114:115]
	v_pk_mul_f32 v[114:115], v[116:117], v[150:151]
	v_add_f32_dpp v28, v28, v28 row_ror:2 row_mask:0xf bank_mask:0xf bound_ctrl:1
	v_lshlrev_b32_e32 v162, 16, v95
	v_and_b32_e32 v163, 0xffff0000, v95
	v_add_f32_dpp v28, v28, v28 row_ror:4 row_mask:0xf bank_mask:0xf bound_ctrl:1
	v_pk_add_f32 v[108:109], v[108:109], v[160:161] neg_lo:[0,1] neg_hi:[0,1]
	v_pk_add_f32 v[110:111], v[110:111], v[162:163] neg_lo:[0,1] neg_hi:[0,1]
	v_add_f32_dpp v28, v28, v28 row_ror:8 row_mask:0xf bank_mask:0xf bound_ctrl:1
	v_max_f32_e32 v28, 0x179abe15, v28
	v_rsq_f32_e32 v28, v28
	v_pk_fma_f32 v[110:111], v[8:9], v[110:111], v[162:163]
	v_pk_fma_f32 v[108:109], v[6:7], v[108:109], v[160:161]
	v_pk_mul_f32 v[150:151], v[116:117], v[28:29] op_sel_hi:[1,0] neg_lo:[0,1] neg_hi:[0,1]
	v_lshlrev_b32_e32 v116, 16, v85
	v_and_b32_e32 v117, 0xffff0000, v85
	v_pk_add_f32 v[112:113], v[112:113], v[116:117] neg_lo:[0,1] neg_hi:[0,1]
	v_pk_mul_f32 v[154:155], v[114:115], v[28:29] op_sel_hi:[1,0]
	v_pk_fma_f32 v[158:159], v[12:13], v[112:113], v[116:117]
	v_pk_mul_f32 v[148:149], v[146:147], v[28:29] op_sel_hi:[1,0] neg_lo:[0,1] neg_hi:[0,1]
	v_pk_mul_f32 v[112:113], v[158:159], v[142:143]
	v_fmac_f32_e32 v156, v24, v112
	v_cvt_f32_f16_sdwa v147, v99 dst_sel:DWORD dst_unused:UNUSED_PAD src0_sel:WORD_1
	v_cvt_f32_f16_e32 v146, v99
	v_fmac_f32_e32 v156, v25, v113
	s_nop 1
	v_add_f32_dpp v114, v156, v156 row_ror:1 row_mask:0xf bank_mask:0xf bound_ctrl:1
	s_nop 1
	v_add_f32_dpp v114, v114, v114 row_ror:2 row_mask:0xf bank_mask:0xf bound_ctrl:1
	s_nop 1
	v_add_f32_dpp v112, v114, v114 row_ror:4 row_mask:0xf bank_mask:0xf bound_ctrl:1
	v_mov_b32_e32 v113, 0
	v_pk_add_f32 v[146:147], v[146:147], 1.0 op_sel_hi:[1,0] neg_lo:[1,0] neg_hi:[1,0]
	s_nop 0
	v_mov_b32_dpp v113, v112 row_ror:8 row_mask:0xf bank_mask:0xf
	v_pk_mul_f32 v[152:153], v[152:153], v[28:29] op_sel_hi:[1,0]
	v_pk_mul_f32 v[156:157], v[118:119], 1.0 op_sel_hi:[1,0]
	v_pk_mul_f32 v[158:159], v[158:159], 1.0 op_sel_hi:[1,0]
	ds_write_b128 v129, v[108:111] offset:1280
	v_pk_mul_f32 v[196:197], v[174:175], v[144:145]
	v_pk_mul_f32 v[198:199], v[176:177], v[146:147]
	v_mov_b32_e32 v200, v196
	v_mov_b32_e32 v201, v197
	v_mov_b32_e32 v202, v198
	v_mov_b32_e32 v203, v199
	v_mov_b32_e32 v208, v196
	v_mov_b32_e32 v209, v197
	v_mov_b32_e32 v210, v198
	v_mov_b32_e32 v211, v199
	v_permlane16_swap_b32 v200, v208
	v_permlane16_swap_b32 v201, v209
	v_permlane16_swap_b32 v202, v210
	v_permlane16_swap_b32 v203, v211
	v_pk_mul_f32 v[204:205], v[200:201], v[208:209]
	v_pk_mul_f32 v[206:207], v[202:203], v[210:211]
	v_mov_b32_e32 v208, v204
	v_mov_b32_e32 v209, v205
	v_mov_b32_e32 v210, v206
	v_mov_b32_e32 v211, v207
	v_permlane32_swap_b32 v204, v208
	v_permlane32_swap_b32 v205, v209
	v_permlane32_swap_b32 v206, v210
	v_permlane32_swap_b32 v207, v211
	v_fma_f32 v200, v200, v235, v236
	v_fma_f32 v201, v201, v235, v236
	v_fma_f32 v202, v202, v235, v236
	v_fma_f32 v203, v203, v235, v236
	v_fma_f32 v208, v204, v237, v238
	v_fma_f32 v209, v205, v237, v238
	v_fma_f32 v210, v206, v237, v238
	v_fma_f32 v211, v207, v237, v238
	v_pk_mul_f32 v[212:213], v[200:201], v[208:209]
	v_pk_mul_f32 v[214:215], v[202:203], v[210:211]
	v_pk_mul_f32 v[216:217], v[212:213], v[174:175]
	v_pk_mul_f32 v[218:219], v[214:215], v[176:177]
	v_pk_mul_f32 v[220:221], v[216:217], v[144:145]
	v_pk_mul_f32 v[222:223], v[218:219], v[146:147]
	v_rcp_f32_e32 v224, v216
	v_rcp_f32_e32 v225, v217
	v_rcp_f32_e32 v226, v218
	v_rcp_f32_e32 v227, v219
	v_rcp_f32_e32 v228, v220
	v_rcp_f32_e32 v229, v221
	v_rcp_f32_e32 v230, v222
	v_rcp_f32_e32 v231, v223
	s_nop 0
	v_pk_mul_f32 v[182:183], v[182:183], v[212:213]
	v_pk_mul_f32 v[184:185], v[184:185], v[214:215]
	v_pk_mul_f32 v[178:179], v[178:179], v[224:225]
	v_pk_mul_f32 v[180:181], v[180:181], v[226:227]
	ds_write_b128 v194, v[178:181] offset:256
	v_pk_mul_f32 v[186:187], v[186:187], v[224:225]
	v_pk_mul_f32 v[188:189], v[188:189], v[226:227]
	ds_write_b128 v194, v[182:185] offset:512
	v_pk_mul_f32 v[190:191], v[190:191], v[216:217]
	v_pk_mul_f32 v[192:193], v[192:193], v[218:219]
	ds_write_b128 v194, v[186:189] offset:768
	v_pk_mul_f32 v[240:241], v[140:141], v[228:229]
	v_pk_mul_f32 v[242:243], v[142:143], v[230:231]
	ds_write_b128 v194, v[190:193] offset:1024
	v_pk_mul_f32 v[244:245], v[148:149], v[216:217]
	v_pk_mul_f32 v[246:247], v[150:151], v[218:219]
	ds_write_b128 v129, v[220:223]
	v_pk_mul_f32 v[196:197], v[152:153], v[228:229]
	v_pk_mul_f32 v[198:199], v[154:155], v[230:231]
	ds_write_b128 v129, v[240:243] offset:256
	v_pk_mul_f32 v[200:201], v[156:157], v[220:221]
	v_pk_mul_f32 v[202:203], v[158:159], v[222:223]
	ds_write_b128 v129, v[244:247] offset:512
	ds_write_b128 v129, v[196:199] offset:768
	ds_write_b128 v129, v[200:203] offset:1024
	s_and_saveexec_b64 s[56:57], s[4:5]
	s_cbranch_execz .LBB0_1123
	s_or_b64 exec, exec, s[56:57]
	s_and_saveexec_b64 s[56:57], s[44:45]
	s_cbranch_execnz .LBB0_1124
